# plus retention units: K/V staging loads issued together instead of 12 + 8 serial round trips
# speedup vs baseline: 1.0058x; 1.0058x over previous
; #define LAS __attribute__((address_space(3)))
; __device__ __forceinline__ float ex2(float x) { return __builtin_amdgcn_exp2f(x); }
; __device__ __forceinline__ void unpack8(const v4u w, float* f) { f[0] = blo(w.x); f[1] = bhi(w.x); f[2] = blo(w.y); f[3] = bhi(w.y); f[4] = blo(w.z); f[5] = bhi(w.z); f[6] = blo(w.w); f[7] = bhi(w.w); }
; __device__ __forceinline__ v4u pack8(const float* f) { v4u w; w.x = pk2(f[0], f[1]); w.y = pk2(f[2], f[3]); w.z = pk2(f[4], f[5]); w.w = pk2(f[6], f[7]); return w; }
; __device__ __forceinline__ void ret_kv_unit(LAS unsigned char* lds, const bf16* Zk  , const bf16* Vp, float* KVC, float lg2  ,
;                                             int t0  , const float* C64, const float* S64, int tid) {
;     ...
;     for (int j = 0; j < 2; ++j) { const int it = tid + 512 * j, r = it >> 3, cc = it & 7, t = t0 + r; float x1[8], x2[8];
;         unpack8(*(const v4u*)(Zk + (size_t)r * NINP + cc * 8), x1); unpack8(*(const v4u*)(Zk + (size_t)r * NINP + 64 + cc * 8), x2);
;         const f32x4 ca = *(const f32x4*)(C64 + t * 64 + cc * 8), cb = *(const f32x4*)(C64 + t * 64 + cc * 8 + 4), sa = *(const f32x4*)(S64 + t * 64 + cc * 8), sb = *(const f32x4*)(S64 + t * 64 + cc * 8 + 4);
;         const float z = (t >= PADR ? RET_KS : 0.f) * ex2((float)(127 - r) * lg2); float o1[8], o2[8];
; #pragma unroll
;         for (int i = 0; i < 8; ++i) { const float c = i < 4 ? ca[i & 3] : cb[i & 3], sn = i < 4 ? sa[i & 3] : sb[i & 3]; o1[i] = (x1[i] * c - x2[i] * sn) * z; o2[i] = (x2[i] * c + x1[i] * sn) * z; }
;         *(LAS v4u*)(lds + KOFF + r * SKk + cc * 16) = pack8(o1); *(LAS v4u*)(lds + KOFF + r * SKk + 128 + cc * 16) = pack8(o2); }
; #pragma unroll
;     for (int j = 0; j < 8; ++j) { const int c = tid + 512 * j, r = c >> 5, cc = c & 31; *(LAS v4u*)(lds + VOFF + r * SVv + cc * 16) = *(const v4u*)(Vp + (size_t)r * NINP + cc * 8); }
.LBB0_636:
	s_and_b32 s6, s13, 31
	s_ashr_i32 s7, s13, 5
	s_ashr_i32 s8, s13, 7
	s_and_b32 s14, s7, 3
	s_mul_hi_i32 s9, s8, 0x1080
	s_mulk_i32 s8, 0x1080
	s_lshl_b32 s15, s6, 7
	s_add_u32 s8, s8, s15
	s_addc_u32 s9, s9, 0
	s_mulk_i32 s9, 0x5c00
	s_mul_hi_u32 s10, s8, 0x5c00
	s_add_i32 s10, s10, s9
	s_mulk_i32 s8, 0x5c00
	v_cvt_f32_ubyte0_e32 v2, s14
	s_add_u32 s8, s0, s8
	v_sub_f32_e32 v2, 0xc0a00000, v2
	s_addc_u32 s9, s12, s10
	s_lshl_b32 s10, s14, 8
	v_exp_f32_e32 v2, v2
	s_add_u32 s10, s8, s10
	s_addc_u32 s11, s9, 0
	v_add_u32_e32 v26, s15, v113
	s_add_u32 s10, s10, 0x1680
	v_lshlrev_b32_e32 v10, 6, v26
	s_addc_u32 s11, s11, 0
	v_sub_f32_e32 v2, 1.0, v2
	v_ashrrev_i32_e32 v11, 31, v10
	v_log_f32_e32 v42, v2
	v_lshl_add_u64 v[2:3], s[10:11], 0, v[70:71]
	v_lshlrev_b64 v[18:19], 2, v[10:11]
	v_lshl_add_u64 v[6:7], v[2:3], 0, v[0:1]
	v_lshl_add_u64 v[14:15], v[66:67], 0, v[18:19]
	v_lshl_add_u64 v[22:23], v[68:69], 0, v[18:19]
	s_barrier
	global_load_dwordx4 v[2:5], v[6:7], off
	s_nop 0
	global_load_dwordx4 v[6:9], v[6:7], off offset:128
	s_nop 0
	global_load_dwordx4 v[10:13], v[14:15], off offset:16
	s_nop 0
	global_load_dwordx4 v[14:17], v[14:15], off
	s_nop 0
	global_load_dwordx4 v[18:21], v[22:23], off offset:16
	s_nop 0
	global_load_dwordx4 v[22:25], v[22:23], off
	v_mul_f32_e32 v27, v42, v114
	v_exp_f32_e32 v28, v27
	v_cmp_lt_i32_e32 vcc, s94, v26
	s_lshl_b32 s16, s14, 9
	s_add_u32 s8, s8, s16
	v_cndmask_b32_e32 v26, 0, v234, vcc
	s_addc_u32 s9, s9, 0
	v_mov_b32_e32 v93, v1
	v_lshl_add_u64 v[218:219], s[8:9], 0, v[92:93]
	v_lshl_add_u64 v[218:219], v[218:219], 0, s[66:67]
	v_lshl_add_u64 v[220:221], v[218:219], 0, v[74:75]
	global_load_dwordx4 v[186:189], v[220:221], off
	v_lshl_add_u64 v[220:221], v[218:219], 0, v[76:77]
	global_load_dwordx4 v[190:193], v[220:221], off
	v_lshl_add_u64 v[220:221], v[218:219], 0, v[78:79]
	global_load_dwordx4 v[194:197], v[220:221], off
	v_lshl_add_u64 v[220:221], v[218:219], 0, v[80:81]
	global_load_dwordx4 v[198:201], v[220:221], off
	v_lshl_add_u64 v[220:221], v[218:219], 0, v[82:83]
	global_load_dwordx4 v[202:205], v[220:221], off
	v_lshl_add_u64 v[220:221], v[218:219], 0, v[84:85]
	global_load_dwordx4 v[206:209], v[220:221], off
	v_lshl_add_u64 v[220:221], v[218:219], 0, v[86:87]
	global_load_dwordx4 v[210:213], v[220:221], off
	v_lshl_add_u64 v[220:221], v[218:219], 0, v[88:89]
	global_load_dwordx4 v[214:217], v[220:221], off
	s_mul_i32 s7, s7, 33
	s_add_i32 s6, s7, s6
	s_ashr_i32 s7, s6, 31
	s_lshl_b64 s[6:7], s[6:7], 17
	v_lshl_add_u64 v[110:111], v[90:91], 0, s[6:7]
	v_mov_b32_e32 v95, v1
	v_mov_b32_e32 v97, v1
	v_mov_b32_e32 v99, v1
	v_mov_b32_e32 v101, v1
	v_mov_b32_e32 v103, v1
	v_mov_b32_e32 v105, v1
	v_mov_b32_e32 v107, v1
	v_mov_b32_e32 v109, v1
	s_add_i32 s13, s13, s50
	s_waitcnt vmcnt(13)
	v_lshlrev_b32_e32 v30, 16, v2
	s_waitcnt vmcnt(12)
	v_lshlrev_b32_e32 v31, 16, v6
	s_waitcnt vmcnt(10)
	v_mov_b32_e32 v32, v14
	s_waitcnt vmcnt(8)
	v_mov_b32_e32 v33, v22
	v_mov_b32_e32 v34, v22
	v_mov_b32_e32 v35, v14
	v_pk_mul_f32 v[32:33], v[32:33], v[30:31]
	v_pk_mul_f32 v[30:31], v[34:35], v[30:31]
	v_and_b32_e32 v35, 0xffff0000, v6
	v_and_b32_e32 v34, 0xffff0000, v2
	v_mov_b32_e32 v22, v15
	v_mov_b32_e32 v14, v23
	v_pk_mul_f32 v[36:37], v[22:23], v[34:35]
	v_pk_mul_f32 v[14:15], v[14:15], v[34:35]
	v_lshlrev_b32_e32 v23, 16, v7
	v_lshlrev_b32_e32 v22, 16, v3
	v_mov_b32_e32 v34, v16
	v_mov_b32_e32 v35, v24
	v_mov_b32_e32 v38, v24
	v_mov_b32_e32 v39, v16
	v_and_b32_e32 v7, 0xffff0000, v7
	v_and_b32_e32 v6, 0xffff0000, v3
	v_mov_b32_e32 v24, v17
	v_mov_b32_e32 v16, v25
	v_pk_mul_f32 v[34:35], v[34:35], v[22:23]
	v_pk_mul_f32 v[22:23], v[38:39], v[22:23]
	v_pk_mul_f32 v[2:3], v[24:25], v[6:7]
	v_pk_mul_f32 v[6:7], v[16:17], v[6:7]
	v_lshlrev_b32_e32 v17, 16, v8
	v_lshlrev_b32_e32 v16, 16, v4
	v_mov_b32_e32 v24, v10
	v_mov_b32_e32 v25, v18
	v_mov_b32_e32 v38, v18
	v_mov_b32_e32 v39, v10
	v_pk_mul_f32 v[24:25], v[24:25], v[16:17]
	v_pk_mul_f32 v[16:17], v[38:39], v[16:17]
	v_and_b32_e32 v39, 0xffff0000, v8
	v_and_b32_e32 v38, 0xffff0000, v4
	v_mov_b32_e32 v18, v11
	v_pk_mul_f32 v[40:41], v[18:19], v[38:39]
	v_mov_b32_e32 v10, v19
	v_lshlrev_b32_e32 v19, 16, v5
	v_mov_b32_e32 v27, v12
	v_mov_b32_e32 v29, v19
	v_pk_mul_f32 v[26:27], v[26:27], v[28:29]
	v_sub_f32_e32 v4, v32, v33
	v_mul_f32_e32 v8, v26, v4
	v_add_f32_e32 v4, v31, v30
	v_mul_f32_e32 v28, v26, v4
	v_sub_f32_e32 v4, v36, v37
	v_mul_f32_e32 v29, v26, v4
	v_add_f32_e32 v4, v15, v14
	v_mul_f32_e32 v14, v26, v4
	v_sub_f32_e32 v4, v34, v35
	v_sub_f32_e32 v2, v2, v3
	v_mul_f32_e32 v15, v26, v4
	v_add_f32_e32 v4, v23, v22
	v_mul_f32_e32 v23, v26, v2
	v_add_f32_e32 v2, v7, v6
	v_mul_f32_e32 v6, v26, v2
	v_sub_f32_e32 v2, v24, v25
	v_mul_f32_e32 v7, v26, v2
	v_add_f32_e32 v2, v17, v16
	v_pk_mul_f32 v[10:11], v[10:11], v[38:39]
	v_mul_f32_e32 v16, v26, v2
	v_sub_f32_e32 v2, v40, v41
	v_lshlrev_b32_e32 v18, 16, v9
	v_mul_f32_e32 v17, v26, v2
	v_add_f32_e32 v2, v11, v10
	v_mul_f32_e32 v10, v26, v2
	v_fma_f32 v2, -v20, v18, v27
	v_mul_f32_e32 v11, v26, v2
	v_mov_b32_e32 v2, v12
	v_mov_b32_e32 v3, v20
	v_pk_mul_f32 v[2:3], v[2:3], v[18:19]
	v_mov_b32_e32 v20, v13
	v_add_f32_e32 v2, v2, v3
	v_mul_f32_e32 v18, v26, v2
	v_and_b32_e32 v3, 0xffff0000, v9
	v_and_b32_e32 v2, 0xffff0000, v5
	v_mov_b32_e32 v12, v21
	v_mul_f32_e32 v22, v26, v4
	v_pk_mul_f32 v[4:5], v[20:21], v[2:3]
	v_pk_mul_f32 v[2:3], v[12:13], v[2:3]
	v_sub_f32_e32 v4, v4, v5
	v_add_f32_e32 v2, v3, v2
	v_mul_f32_e32 v5, v26, v4
	v_mul_f32_e32 v9, v26, v2
	v_cvt_pk_bf16_f32 v4, v7, v17
	v_add_u32_e32 v26, s15, v115
	v_cvt_pk_bf16_f32 v2, v8, v29
	v_cvt_pk_bf16_f32 v3, v15, v23
	v_cvt_pk_bf16_f32 v5, v11, v5
	ds_write_b128 v121, v[2:5]
	v_cvt_pk_bf16_f32 v4, v16, v10
	v_lshlrev_b32_e32 v10, 6, v26
	v_cvt_pk_bf16_f32 v2, v28, v14
	v_cvt_pk_bf16_f32 v3, v22, v6
	v_ashrrev_i32_e32 v11, 31, v10
	v_cvt_pk_bf16_f32 v5, v18, v9
	ds_write_b128 v121, v[2:5] offset:128
	v_lshl_add_u64 v[2:3], s[10:11], 0, v[72:73]
	v_lshlrev_b64 v[18:19], 2, v[10:11]
	v_lshl_add_u64 v[6:7], v[2:3], 0, v[0:1]
	v_lshl_add_u64 v[14:15], v[66:67], 0, v[18:19]
	v_lshl_add_u64 v[22:23], v[68:69], 0, v[18:19]
	global_load_dwordx4 v[2:5], v[6:7], off
	s_nop 0
	global_load_dwordx4 v[6:9], v[6:7], off offset:128
	s_nop 0
	global_load_dwordx4 v[10:13], v[14:15], off
	s_nop 0
	global_load_dwordx4 v[14:17], v[14:15], off offset:16
	s_nop 0
	global_load_dwordx4 v[18:21], v[22:23], off
	s_nop 0
	global_load_dwordx4 v[22:25], v[22:23], off offset:16
	v_mul_f32_e32 v27, v42, v116
	v_exp_f32_e32 v28, v27
	v_cmp_lt_i32_e32 vcc, s94, v26
	v_readfirstlane_b32 s10, v112
	s_waitcnt vmcnt(5)
; #define LAS __attribute__((address_space(3)))
; __device__ __forceinline__ float ex2(float x) { return __builtin_amdgcn_exp2f(x); }
; __device__ __forceinline__ void ret_kv_unit(LAS unsigned char* lds, const bf16* Zk  , const bf16* Vp, float* KVC, float lg2  ,
;                                             int t0  , const float* C64, const float* S64, int tid) {
;     ...
;     for (int j = 0; j < 2; ++j) { const int it = tid + 512 * j, r = it >> 3, cc = it & 7, t = t0 + r; float x1[8], x2[8];
;         unpack8(*(const v4u*)(Zk + (size_t)r * NINP + cc * 8), x1); unpack8(*(const v4u*)(Zk + (size_t)r * NINP + 64 + cc * 8), x2);
;         const f32x4 ca = *(const f32x4*)(C64 + t * 64 + cc * 8), cb = *(const f32x4*)(C64 + t * 64 + cc * 8 + 4), sa = *(const f32x4*)(S64 + t * 64 + cc * 8), sb = *(const f32x4*)(S64 + t * 64 + cc * 8 + 4);
;         const float z = (t >= PADR ? RET_KS : 0.f) * ex2((float)(127 - r) * lg2); float o1[8], o2[8];
; #pragma unroll
;         for (int i = 0; i < 8; ++i) { const float c = i < 4 ? ca[i & 3] : cb[i & 3], sn = i < 4 ? sa[i & 3] : sb[i & 3]; o1[i] = (x1[i] * c - x2[i] * sn) * z; o2[i] = (x2[i] * c + x1[i] * sn) * z; }
;         *(LAS v4u*)(lds + KOFF + r * SKk + cc * 16) = pack8(o1); *(LAS v4u*)(lds + KOFF + r * SKk + 128 + cc * 16) = pack8(o2); }
; #pragma unroll
;     for (int j = 0; j < 8; ++j) { const int c = tid + 512 * j, r = c >> 5, cc = c & 31; *(LAS v4u*)(lds + VOFF + r * SVv + cc * 16) = *(const v4u*)(Vp + (size_t)r * NINP + cc * 8); }
;     __syncthreads();
;     f32x4 acc[2][8];
; #pragma unroll
;     for (int i = 0; i < 2; ++i)
; #pragma unroll
;         for (int j = 0; j < 8; ++j) acc[i][j] = (f32x4){0.f, 0.f, 0.f, 0.f};
;     const int roff = 8 * g + (c16 >> 2), coff = 4 * (c16 & 3);
; #pragma unroll
;     for (int ks = 0; ks < 4; ++ks) {
;         bf16x8 af[2];
; #pragma unroll
;         for (int i = 0; i < 2; ++i) { const LAS unsigned char* p = lds + VOFF + (32 * ks + roff) * SVv + (16 * (2 * w + i) + coff) * 2; af[i] = cat4(tr_read(p), tr_read(p + 4 * SVv)); }
; #pragma unroll
;         for (int j = 0; j < 8; ++j) { const LAS unsigned char* p = lds + KOFF + (32 * ks + roff) * SKk + (16 * j + coff) * 2; const bf16x8 bfr = cat4(tr_read(p), tr_read(p + 4 * SKk));
; #pragma unroll
;             for (int i = 0; i < 2; ++i) acc[i][j] = MFMA16(af[i], bfr, acc[i][j]); }
	v_lshlrev_b32_e32 v31, 16, v5
	s_waitcnt vmcnt(4)
	v_lshlrev_b32_e32 v30, 16, v9
	s_waitcnt vmcnt(2)
	v_mov_b32_e32 v32, v16
	s_waitcnt vmcnt(0)
	v_mov_b32_e32 v33, v24
	v_cndmask_b32_e32 v26, 0, v234, vcc
	v_pk_mul_f32 v[32:33], v[32:33], v[30:31]
	v_mov_b32_e32 v27, v16
	v_mov_b32_e32 v29, v31
	v_pk_mul_f32 v[26:27], v[26:27], v[28:29]
	v_add_f32_e32 v16, v32, v33
	v_mul_f32_e32 v32, v26, v16
	v_fma_f32 v16, -v24, v30, v27
	v_and_b32_e32 v29, 0xffff0000, v8
	v_and_b32_e32 v28, 0xffff0000, v4
	v_mov_b32_e32 v30, v23
	v_mov_b32_e32 v31, v15
	v_pk_mul_f32 v[30:31], v[30:31], v[28:29]
	v_mul_f32_e32 v27, v26, v16
	v_add_f32_e32 v16, v31, v30
	v_mov_b32_e32 v30, v15
	v_mov_b32_e32 v31, v23
	v_pk_mul_f32 v[28:29], v[30:31], v[28:29]
	v_mov_b32_e32 v23, v14
	v_sub_f32_e32 v15, v28, v29
	v_lshlrev_b32_e32 v29, 16, v8
	v_lshlrev_b32_e32 v28, 16, v4
	v_mul_f32_e32 v34, v26, v15
	v_pk_mul_f32 v[30:31], v[22:23], v[28:29]
	v_mov_b32_e32 v15, v22
	v_add_f32_e32 v4, v31, v30
	v_pk_mul_f32 v[14:15], v[14:15], v[28:29]
	v_mul_f32_e32 v8, v26, v4
	v_sub_f32_e32 v4, v14, v15
	v_and_b32_e32 v15, 0xffff0000, v7
	v_and_b32_e32 v14, 0xffff0000, v3
	v_mov_b32_e32 v22, v21
	v_mov_b32_e32 v23, v13
	v_pk_mul_f32 v[22:23], v[22:23], v[14:15]
	v_mul_f32_e32 v28, v26, v4
	v_add_f32_e32 v4, v23, v22
	v_mov_b32_e32 v22, v13
	v_mov_b32_e32 v23, v21
	v_pk_mul_f32 v[14:15], v[22:23], v[14:15]
	v_mul_f32_e32 v29, v26, v4
	v_sub_f32_e32 v4, v14, v15
	v_lshlrev_b32_e32 v15, 16, v7
	v_lshlrev_b32_e32 v14, 16, v3
	v_mov_b32_e32 v21, v12
	v_pk_mul_f32 v[22:23], v[20:21], v[14:15]
	v_mov_b32_e32 v13, v20
	v_add_f32_e32 v3, v23, v22
	v_pk_mul_f32 v[12:13], v[12:13], v[14:15]
	v_mul_f32_e32 v21, v26, v3
	v_sub_f32_e32 v3, v12, v13
	v_and_b32_e32 v13, 0xffff0000, v6
	v_and_b32_e32 v12, 0xffff0000, v2
	v_mov_b32_e32 v14, v19
	v_mov_b32_e32 v15, v11
	v_pk_mul_f32 v[14:15], v[14:15], v[12:13]
	v_mul_f32_e32 v20, v26, v3
	v_add_f32_e32 v3, v15, v14
	v_mov_b32_e32 v14, v11
	v_mov_b32_e32 v15, v19
	v_pk_mul_f32 v[12:13], v[14:15], v[12:13]
	v_mul_f32_e32 v22, v26, v3
	v_sub_f32_e32 v3, v12, v13
	v_mul_f32_e32 v12, v26, v3
	v_lshlrev_b32_e32 v3, 16, v6
	v_lshlrev_b32_e32 v2, 16, v2
	v_mov_b32_e32 v19, v10
	v_mov_b32_e32 v11, v18
	v_pk_mul_f32 v[6:7], v[18:19], v[2:3]
	v_pk_mul_f32 v[2:3], v[10:11], v[2:3]
	v_mul_f32_e32 v33, v26, v16
	v_sub_f32_e32 v2, v2, v3
	v_mul_f32_e32 v30, v26, v4
	v_add_f32_e32 v4, v7, v6
	v_mul_f32_e32 v7, v26, v2
	v_and_b32_e32 v3, 0xffff0000, v9
	v_and_b32_e32 v2, 0xffff0000, v5
	v_mov_b32_e32 v24, v17
	v_mov_b32_e32 v16, v25
	v_mul_f32_e32 v6, v26, v4
	v_pk_mul_f32 v[4:5], v[24:25], v[2:3]
	v_pk_mul_f32 v[2:3], v[16:17], v[2:3]
	v_sub_f32_e32 v4, v4, v5
	v_add_f32_e32 v2, v3, v2
	v_mul_f32_e32 v5, v26, v4
	v_mul_f32_e32 v9, v26, v2
	v_cvt_pk_bf16_f32 v2, v7, v12
	v_cvt_pk_bf16_f32 v3, v20, v30
	v_cvt_pk_bf16_f32 v4, v28, v34
	v_cvt_pk_bf16_f32 v5, v27, v5
	ds_write_b128 v122, v[2:5]
	v_cvt_pk_bf16_f32 v2, v6, v22
	v_cvt_pk_bf16_f32 v3, v21, v29
	v_cvt_pk_bf16_f32 v4, v8, v33
	v_cvt_pk_bf16_f32 v5, v32, v9
	ds_write_b128 v122, v[2:5] offset:128
	s_and_b32 s8, s10, 0xffffffc0
	s_waitcnt vmcnt(0)
	ds_write_b128 v123, v[186:189] offset:36864
	ds_write_b128 v124, v[190:193] offset:36864
	ds_write_b128 v125, v[194:197] offset:36864
	ds_write_b128 v126, v[198:201] offset:36864
	ds_write_b128 v127, v[202:205] offset:36864
	ds_write_b128 v128, v[206:209] offset:36864
	ds_write_b128 v129, v[210:213] offset:36864
	ds_write_b128 v130, v[214:217] offset:36864
	v_add_u32_e32 v2, s8, v117
	s_waitcnt lgkmcnt(0)
	s_barrier
	ds_read_b64_tr_b16 v[6:7], v2 offset:39040
	ds_read_b64_tr_b16 v[4:5], v2 offset:36864
	ds_read_b64_tr_b16 v[8:9], v2 offset:36896
	ds_read_b64_tr_b16 v[10:11], v2 offset:39072
	ds_read_b64_tr_b16 v[14:15], v131 offset:1152
	ds_read_b64_tr_b16 v[12:13], v131
	ds_read_b64_tr_b16 v[16:17], v131 offset:32
	ds_read_b64_tr_b16 v[18:19], v131 offset:1184
	ds_read_b64_tr_b16 v[28:29], v131 offset:64
	ds_read_b64_tr_b16 v[30:31], v131 offset:1216
	ds_read_b64_tr_b16 v[36:37], v131 offset:96
	ds_read_b64_tr_b16 v[38:39], v131 offset:1248
	ds_read_b64_tr_b16 v[44:45], v131 offset:128
	ds_read_b64_tr_b16 v[46:47], v131 offset:1280
	ds_read_b64_tr_b16 v[52:53], v131 offset:160
	ds_read_b64_tr_b16 v[54:55], v131 offset:1312
	ds_read_b64_tr_b16 v[60:61], v131 offset:192
	ds_read_b64_tr_b16 v[62:63], v131 offset:1344
	ds_read_b64_tr_b16 v[136:137], v131 offset:224
	ds_read_b64_tr_b16 v[138:139], v131 offset:1376
	s_waitcnt lgkmcnt(14)
	v_mfma_f32_16x16x32_bf16 v[20:23], v[4:7], v[12:15], 0
	v_mfma_f32_16x16x32_bf16 v[12:15], v[8:11], v[12:15], 0
	s_waitcnt lgkmcnt(12)
	v_mfma_f32_16x16x32_bf16 v[24:27], v[4:7], v[16:19], 0
	v_mfma_f32_16x16x32_bf16 v[16:19], v[8:11], v[16:19], 0
	s_waitcnt lgkmcnt(10)
	v_mfma_f32_16x16x32_bf16 v[32:35], v[4:7], v[28:31], 0
	v_mfma_f32_16x16x32_bf16 v[28:31], v[8:11], v[28:31], 0
	s_waitcnt lgkmcnt(8)
	v_mfma_f32_16x16x32_bf16 v[40:43], v[4:7], v[36:39], 0
	v_mfma_f32_16x16x32_bf16 v[36:39], v[8:11], v[36:39], 0
	s_waitcnt lgkmcnt(6)
	v_mfma_f32_16x16x32_bf16 v[48:51], v[4:7], v[44:47], 0
	v_mfma_f32_16x16x32_bf16 v[44:47], v[8:11], v[44:47], 0
	s_waitcnt lgkmcnt(4)
	v_mfma_f32_16x16x32_bf16 v[56:59], v[4:7], v[52:55], 0
	v_mfma_f32_16x16x32_bf16 v[52:55], v[8:11], v[52:55], 0
	s_waitcnt lgkmcnt(2)
	v_mfma_f32_16x16x32_bf16 v[132:135], v[4:7], v[60:63], 0
	v_mfma_f32_16x16x32_bf16 v[60:63], v[8:11], v[60:63], 0
	s_waitcnt lgkmcnt(0)
; #define LAS __attribute__((address_space(3)))
; __device__ __forceinline__ s16x4 tr_read(LAS const unsigned char* p) { return __builtin_bit_cast(s16x4, __builtin_amdgcn_ds_read_tr16_b64_v4i16((LAS v4i16_t*)p)); }
; #define MFMA16(a, b, c) __builtin_amdgcn_mfma_f32_16x16x32_bf16((a), (b), (c), 0, 0, 0)
; __device__ __forceinline__ void ret_kv_unit(LAS unsigned char* lds, const bf16* Zk  , const bf16* Vp, float* KVC, float lg2  ,
;                                             int t0  , const float* C64, const float* S64, int tid) {
;     ...
;     const int roff = 8 * g + (c16 >> 2), coff = 4 * (c16 & 3);
; #pragma unroll
;     for (int ks = 0; ks < 4; ++ks) {
;         bf16x8 af[2];
; #pragma unroll
;         for (int i = 0; i < 2; ++i) { const LAS unsigned char* p = lds + VOFF + (32 * ks + roff) * SVv + (16 * (2 * w + i) + coff) * 2; af[i] = cat4(tr_read(p), tr_read(p + 4 * SVv)); }
; #pragma unroll
;         for (int j = 0; j < 8; ++j) { const LAS unsigned char* p = lds + KOFF + (32 * ks + roff) * SKk + (16 * j + coff) * 2; const bf16x8 bfr = cat4(tr_read(p), tr_read(p + 4 * SKk));
; #pragma unroll
;             for (int i = 0; i < 2; ++i) acc[i][j] = MFMA16(af[i], bfr, acc[i][j]); }
	v_mfma_f32_16x16x32_bf16 v[2:5], v[4:7], v[136:139], 0
	v_mfma_f32_16x16x32_bf16 v[6:9], v[8:11], v[136:139], 0
	v_add_u32_e32 v10, s8, v118
	ds_read_b64_tr_b16 v[138:139], v10 offset:39040
	ds_read_b64_tr_b16 v[136:137], v10 offset:36864
	ds_read_b64_tr_b16 v[140:141], v10 offset:36896
	ds_read_b64_tr_b16 v[142:143], v10 offset:39072
	ds_read_b64_tr_b16 v[144:145], v131 offset:9216
	ds_read_b64_tr_b16 v[146:147], v131 offset:10368
	s_waitcnt lgkmcnt(0)
	v_mfma_f32_16x16x32_bf16 v[20:23], v[136:139], v[144:147], v[20:23]
	v_mfma_f32_16x16x32_bf16 v[10:13], v[140:143], v[144:147], v[12:15]
	ds_read_b64_tr_b16 v[144:145], v131 offset:9248
	ds_read_b64_tr_b16 v[146:147], v131 offset:10400
	s_waitcnt lgkmcnt(0)
	v_mfma_f32_16x16x32_bf16 v[24:27], v[136:139], v[144:147], v[24:27]
	v_mfma_f32_16x16x32_bf16 v[14:17], v[140:143], v[144:147], v[16:19]
	ds_read_b64_tr_b16 v[144:145], v131 offset:9280
	ds_read_b64_tr_b16 v[146:147], v131 offset:10432
	s_nop 0
	v_add_u32_e32 v18, s8, v119
	s_waitcnt lgkmcnt(0)
	v_mfma_f32_16x16x32_bf16 v[32:35], v[136:139], v[144:147], v[32:35]
	v_mfma_f32_16x16x32_bf16 v[28:31], v[140:143], v[144:147], v[28:31]
	ds_read_b64_tr_b16 v[144:145], v131 offset:9312
	ds_read_b64_tr_b16 v[146:147], v131 offset:10464
	s_waitcnt lgkmcnt(0)
	v_mfma_f32_16x16x32_bf16 v[40:43], v[136:139], v[144:147], v[40:43]
	v_mfma_f32_16x16x32_bf16 v[36:39], v[140:143], v[144:147], v[36:39]
	ds_read_b64_tr_b16 v[144:145], v131 offset:9344
	ds_read_b64_tr_b16 v[146:147], v131 offset:10496
	s_waitcnt lgkmcnt(0)
	v_mfma_f32_16x16x32_bf16 v[48:51], v[136:139], v[144:147], v[48:51]
	v_mfma_f32_16x16x32_bf16 v[44:47], v[140:143], v[144:147], v[44:47]
	ds_read_b64_tr_b16 v[144:145], v131 offset:9376
	ds_read_b64_tr_b16 v[146:147], v131 offset:10528
	s_waitcnt lgkmcnt(0)
	v_mfma_f32_16x16x32_bf16 v[56:59], v[136:139], v[144:147], v[56:59]
	v_mfma_f32_16x16x32_bf16 v[52:55], v[140:143], v[144:147], v[52:55]
	ds_read_b64_tr_b16 v[144:145], v131 offset:9408
	ds_read_b64_tr_b16 v[146:147], v131 offset:10560
	s_waitcnt lgkmcnt(0)
	v_mfma_f32_16x16x32_bf16 v[132:135], v[136:139], v[144:147], v[132:135]
	v_mfma_f32_16x16x32_bf16 v[60:63], v[140:143], v[144:147], v[60:63]
	ds_read_b64_tr_b16 v[144:145], v131 offset:9440
	ds_read_b64_tr_b16 v[146:147], v131 offset:10592
	s_waitcnt lgkmcnt(0)
	v_mfma_f32_16x16x32_bf16 v[2:5], v[136:139], v[144:147], v[2:5]
	v_mfma_f32_16x16x32_bf16 v[6:9], v[140:143], v[144:147], v[6:9]
	ds_read_b64_tr_b16 v[138:139], v18 offset:39040
	ds_read_b64_tr_b16 v[136:137], v18 offset:36864
	ds_read_b64_tr_b16 v[140:141], v18 offset:36896
	ds_read_b64_tr_b16 v[142:143], v18 offset:39072
	ds_read_b64_tr_b16 v[144:145], v131 offset:18432
	ds_read_b64_tr_b16 v[146:147], v131 offset:19584
	s_waitcnt lgkmcnt(0)
	v_mfma_f32_16x16x32_bf16 v[18:21], v[136:139], v[144:147], v[20:23]
	v_mfma_f32_16x16x32_bf16 v[10:13], v[140:143], v[144:147], v[10:13]
	ds_read_b64_tr_b16 v[144:145], v131 offset:18464
	ds_read_b64_tr_b16 v[146:147], v131 offset:19616
	s_waitcnt lgkmcnt(0)
	v_mfma_f32_16x16x32_bf16 v[22:25], v[136:139], v[144:147], v[24:27]
	v_mfma_f32_16x16x32_bf16 v[14:17], v[140:143], v[144:147], v[14:17]
	ds_read_b64_tr_b16 v[144:145], v131 offset:18496
	ds_read_b64_tr_b16 v[146:147], v131 offset:19648
	s_waitcnt lgkmcnt(0)
	v_mfma_f32_16x16x32_bf16 v[32:35], v[136:139], v[144:147], v[32:35]
	v_mfma_f32_16x16x32_bf16 v[26:29], v[140:143], v[144:147], v[28:31]
	ds_read_b64_tr_b16 v[144:145], v131 offset:18528
	ds_read_b64_tr_b16 v[146:147], v131 offset:19680
	s_waitcnt lgkmcnt(0)
	v_mfma_f32_16x16x32_bf16 v[40:43], v[136:139], v[144:147], v[40:43]
	v_mfma_f32_16x16x32_bf16 v[36:39], v[140:143], v[144:147], v[36:39]
	ds_read_b64_tr_b16 v[144:145], v131 offset:18560
	ds_read_b64_tr_b16 v[146:147], v131 offset:19712
	s_waitcnt lgkmcnt(0)
	v_mfma_f32_16x16x32_bf16 v[148:151], v[136:139], v[144:147], v[48:51]
	v_mfma_f32_16x16x32_bf16 v[144:147], v[140:143], v[144:147], v[44:47]
	s_nop 2
	ds_read_b64_tr_b16 v[44:45], v131 offset:18592
	ds_read_b64_tr_b16 v[46:47], v131 offset:19744
	s_waitcnt lgkmcnt(0)
	v_mfma_f32_16x16x32_bf16 v[152:155], v[136:139], v[44:47], v[56:59]
	v_mfma_f32_16x16x32_bf16 v[156:159], v[140:143], v[44:47], v[52:55]
	ds_read_b64_tr_b16 v[44:45], v131 offset:18624
	ds_read_b64_tr_b16 v[46:47], v131 offset:19776
	s_waitcnt lgkmcnt(0)
; #define LAS __attribute__((address_space(3)))
; __device__ __forceinline__ s16x4 tr_read(LAS const unsigned char* p) { return __builtin_bit_cast(s16x4, __builtin_amdgcn_ds_read_tr16_b64_v4i16((LAS v4i16_t*)p)); }
; #define MFMA16(a, b, c) __builtin_amdgcn_mfma_f32_16x16x32_bf16((a), (b), (c), 0, 0, 0)
; __device__ __forceinline__ void ret_kv_unit(LAS unsigned char* lds, const bf16* Zk  , const bf16* Vp, float* KVC, float lg2  ,
;                                             int t0  , const float* C64, const float* S64, int tid) {
;     ...
;     for (int ks = 0; ks < 4; ++ks) {
;         bf16x8 af[2];
; #pragma unroll
;         for (int i = 0; i < 2; ++i) { const LAS unsigned char* p = lds + VOFF + (32 * ks + roff) * SVv + (16 * (2 * w + i) + coff) * 2; af[i] = cat4(tr_read(p), tr_read(p + 4 * SVv)); }
; #pragma unroll
;         for (int j = 0; j < 8; ++j) { const LAS unsigned char* p = lds + KOFF + (32 * ks + roff) * SKk + (16 * j + coff) * 2; const bf16x8 bfr = cat4(tr_read(p), tr_read(p + 4 * SKk));
; #pragma unroll
;             for (int i = 0; i < 2; ++i) acc[i][j] = MFMA16(af[i], bfr, acc[i][j]); }
;     }
; #pragma unroll
;     for (int i = 0; i < 2; ++i)
; #pragma unroll
;         for (int j = 0; j < 8; ++j) *(f32x4*)(KVC + (size_t)(16 * j + c16) * 256 + 16 * (2 * w + i) + 4 * g) = acc[i][j];
	v_mfma_f32_16x16x32_bf16 v[132:135], v[136:139], v[44:47], v[132:135]
	v_mfma_f32_16x16x32_bf16 v[160:163], v[140:143], v[44:47], v[60:63]
	ds_read_b64_tr_b16 v[44:45], v131 offset:18656
	ds_read_b64_tr_b16 v[46:47], v131 offset:19808
	s_waitcnt lgkmcnt(0)
	v_mfma_f32_16x16x32_bf16 v[136:139], v[136:139], v[44:47], v[2:5]
	s_nop 2
	v_add_u32_e32 v2, s8, v120
	ds_read_b64_tr_b16 v[166:167], v2 offset:39040
	ds_read_b64_tr_b16 v[164:165], v2 offset:36864
	ds_read_b64_tr_b16 v[182:183], v2 offset:36896
	ds_read_b64_tr_b16 v[184:185], v2 offset:39072
	ds_read_b64_tr_b16 v[2:3], v131 offset:27648
	ds_read_b64_tr_b16 v[4:5], v131 offset:28800
	v_mfma_f32_16x16x32_bf16 v[140:143], v[140:143], v[44:47], v[6:9]
	s_nop 2
	ds_read_b64_tr_b16 v[6:7], v131 offset:27680
	ds_read_b64_tr_b16 v[8:9], v131 offset:28832
	s_ashr_i32 s8, s10, 1
	s_andn2_b32 s8, s8, 31
	s_waitcnt lgkmcnt(2)
	v_mfma_f32_16x16x32_bf16 v[62:65], v[164:167], v[2:5], v[18:21]
	s_ashr_i32 s9, s8, 31
	v_lshl_add_u64 v[110:111], s[8:9], 2, v[110:111]
	s_cmpk_gt_i32 s13, 0xff
	v_mfma_f32_16x16x32_bf16 v[2:5], v[182:185], v[2:5], v[10:13]
	s_nop 2
	ds_read_b64_tr_b16 v[10:11], v131 offset:27712
	ds_read_b64_tr_b16 v[12:13], v131 offset:28864
	s_waitcnt lgkmcnt(2)
	v_mfma_f32_16x16x32_bf16 v[58:61], v[164:167], v[6:9], v[22:25]
	v_mfma_f32_16x16x32_bf16 v[6:9], v[182:185], v[6:9], v[14:17]
	s_nop 2
	ds_read_b64_tr_b16 v[14:15], v131 offset:27744
	ds_read_b64_tr_b16 v[16:17], v131 offset:28896
	ds_read_b64_tr_b16 v[18:19], v131 offset:27776
	ds_read_b64_tr_b16 v[20:21], v131 offset:28928
	ds_read_b64_tr_b16 v[22:23], v131 offset:27808
	ds_read_b64_tr_b16 v[24:25], v131 offset:28960
	s_waitcnt lgkmcnt(6)
	v_mfma_f32_16x16x32_bf16 v[50:53], v[164:167], v[10:13], v[32:35]
	v_mfma_f32_16x16x32_bf16 v[10:13], v[182:185], v[10:13], v[26:29]
	s_nop 2
	ds_read_b64_tr_b16 v[26:27], v131 offset:27840
	ds_read_b64_tr_b16 v[28:29], v131 offset:28992
	ds_read_b64_tr_b16 v[30:31], v131 offset:27872
	ds_read_b64_tr_b16 v[32:33], v131 offset:29024
	s_waitcnt lgkmcnt(8)
	v_mfma_f32_16x16x32_bf16 v[54:57], v[164:167], v[14:17], v[40:43]
	v_mfma_f32_16x16x32_bf16 v[14:17], v[182:185], v[14:17], v[36:39]
	s_waitcnt lgkmcnt(2)
	v_mfma_f32_16x16x32_bf16 v[38:41], v[164:167], v[26:29], v[132:135]
	s_nop 2
	v_lshl_add_u64 v[132:133], v[110:111], 0, v[94:95]
	v_mfma_f32_16x16x32_bf16 v[46:49], v[164:167], v[18:21], v[148:151]
	global_store_dwordx4 v[132:133], v[62:65], off
	global_store_dwordx4 v[132:133], v[2:5], off offset:64
	s_nop 0
	v_lshl_add_u64 v[62:63], v[110:111], 0, v[96:97]
	v_mfma_f32_16x16x32_bf16 v[42:45], v[164:167], v[22:25], v[152:155]
	global_store_dwordx4 v[62:63], v[58:61], off
	s_nop 1
	v_lshl_add_u64 v[58:59], v[110:111], 0, v[98:99]
	global_store_dwordx4 v[58:59], v[50:53], off
	s_waitcnt lgkmcnt(0)
	v_mfma_f32_16x16x32_bf16 v[34:37], v[164:167], v[30:33], v[136:139]
	v_lshl_add_u64 v[50:51], v[110:111], 0, v[100:101]
	global_store_dwordx4 v[50:51], v[54:57], off
	v_lshl_add_u64 v[50:51], v[110:111], 0, v[102:103]
	global_store_dwordx4 v[50:51], v[46:49], off
	v_mfma_f32_16x16x32_bf16 v[18:21], v[182:185], v[18:21], v[144:147]
	s_nop 0
	v_lshl_add_u64 v[46:47], v[110:111], 0, v[104:105]
	global_store_dwordx4 v[46:47], v[42:45], off
	v_mfma_f32_16x16x32_bf16 v[22:25], v[182:185], v[22:25], v[156:159]
	s_nop 0
	v_lshl_add_u64 v[42:43], v[110:111], 0, v[106:107]
	global_store_dwordx4 v[42:43], v[38:41], off
	v_mfma_f32_16x16x32_bf16 v[26:29], v[182:185], v[26:29], v[160:163]
	s_nop 0
	v_lshl_add_u64 v[38:39], v[110:111], 0, v[108:109]
	global_store_dwordx4 v[38:39], v[34:37], off
	v_mfma_f32_16x16x32_bf16 v[30:33], v[182:185], v[30:33], v[140:143]
	s_nop 0
	v_lshl_add_u64 v[34:35], v[110:111], 0, 64
	v_lshl_add_u64 v[2:3], v[34:35], 0, v[96:97]
	global_store_dwordx4 v[2:3], v[6:9], off
	v_lshl_add_u64 v[2:3], v[34:35], 0, v[98:99]
	global_store_dwordx4 v[2:3], v[10:13], off
	v_lshl_add_u64 v[2:3], v[34:35], 0, v[100:101]
	global_store_dwordx4 v[2:3], v[14:17], off
	v_lshl_add_u64 v[2:3], v[34:35], 0, v[102:103]
	global_store_dwordx4 v[2:3], v[18:21], off
	v_lshl_add_u64 v[2:3], v[34:35], 0, v[104:105]
	global_store_dwordx4 v[2:3], v[22:25], off
	v_lshl_add_u64 v[2:3], v[34:35], 0, v[106:107]
	global_store_dwordx4 v[2:3], v[26:29], off
	v_lshl_add_u64 v[2:3], v[34:35], 0, v[108:109]
	global_store_dwordx4 v[2:3], v[30:33], off
	s_cbranch_scc0 .LBB0_636

; #define LAS __attribute__((address_space(3)))
; __device__ __forceinline__ void ret_out_unit(LAS unsigned char* lds, const bf16* Qp, const bf16* Kp, const bf16* Vp, const bf16* Sp  , const bf16* Gp  ,
;                                              gfp gn  , bf16* Op, float lg2, int tid) {
;     ...
;     const int lane = tid & 63, w = __builtin_amdgcn_readfirstlane(tid >> 6), g = lane >> 4, c16 = lane & 15, ql = 16 * w + c16;
; #pragma unroll
;     for (int j = 0; j < 4; ++j) { const int c = tid + 512 * j, r = c >> 4, cc = c & 15; *(LAS v4u*)(lds + KOFF + r * SKk + cc * 16) = *(const v4u*)(Kp + (size_t)r * 512 + cc * 8); }
; #pragma unroll
;     for (int j = 0; j < 8; ++j) { const int c = tid + 512 * j, r = c >> 5, cc = c & 31; *(LAS v4u*)(lds + VOFF + r * SVv + cc * 16) = *(const v4u*)(Vp + (size_t)r * NINP + cc * 8); }
;     bf16x8 qf[4];
; #pragma unroll
;     for (int ks = 0; ks < 4; ++ks) qf[ks] = *(const bf16x8*)(Qp + (size_t)ql * 512 + 32 * ks + 8 * g);
;     v2u gwv[16];
; #pragma unroll
;     for (int n = 0; n < 16; ++n) gwv[n] = *(const v2u*)(Gp + (size_t)ql * NINP + 16 * n + 4 * g);
;     __syncthreads();
.LBB0_761:
	s_or_b64 exec, exec, s[8:9]
	v_mov_b32_e32 v0, s88
	s_waitcnt lgkmcnt(0)
	s_barrier
	ds_read_b32 v0, v0
	s_movk_i32 s0, 0x107
	s_mov_b64 s[8:9], -1
	s_waitcnt lgkmcnt(0)
	v_cmp_lt_i32_e32 vcc, s0, v0
	v_readfirstlane_b32 s16, v0
	s_cbranch_vccnz .LBB0_756
	s_mul_hi_i32 s0, s16, 0x3e0f83e1
	s_lshr_b32 s8, s0, 31
	s_ashr_i32 s0, s0, 3
	s_add_i32 s0, s0, s8
	s_mul_i32 s8, s0, 33
	s_sub_i32 s8, s16, s8
	s_ashr_i32 s9, s0, 2
	s_lshl_b32 s8, s8, 7
	s_and_b32 s17, s0, 3
	s_mul_hi_i32 s0, s9, 0x1080
	s_mulk_i32 s9, 0x1080
	s_ashr_i32 s15, s8, 31
	s_add_u32 s14, s9, s8
	s_addc_u32 s15, s0, s15
	v_readlane_b32 s33, v247, 43
	v_mov_b32_e32 v18, v196
	s_lshl_b64 s[18:19], s[14:15], 10
	v_mov_b32_e32 v0, s33
	s_add_u32 s8, s22, s18
	ds_read_b64 v[2:3], v0
	v_cvt_f32_ubyte0_e32 v0, s17
	s_addc_u32 s9, s23, s19
	s_lshl_b32 s0, s17, 8
	v_sub_f32_e32 v0, 0xc0a00000, v0
	s_add_u32 s8, s8, s0
	v_exp_f32_e32 v0, v0
	s_addc_u32 s9, s9, 0
	s_add_u32 s18, s24, s18
	s_addc_u32 s19, s25, s19
	s_add_u32 s36, s18, s0
	v_sub_f32_e32 v0, 1.0, v0
	v_and_b32_e32 v19, 15, v18
	v_ashrrev_i32_e32 v8, 4, v18
	s_addc_u32 s37, s19, 0
	v_log_f32_e32 v136, v0
	v_lshlrev_b32_e32 v0, 4, v19
	v_ashrrev_i32_e32 v9, 31, v8
	s_waitcnt lgkmcnt(0)
	v_readfirstlane_b32 s33, v2
	v_readfirstlane_b32 s34, v3
	v_lshl_add_u64 v[6:7], s[36:37], 0, v[0:1]
	v_lshlrev_b64 v[2:3], 10, v[8:9]
	v_lshl_add_u64 v[2:3], v[6:7], 0, v[2:3]
	global_load_dwordx4 v[26:29], v[2:3], off
	v_add_u32_e32 v0, 0, v0
	v_mad_u32_u24 v74, v8, s77, v0
	v_add_u32_e32 v10, 0x200, v18
	v_add_u32_e32 v11, 0x400, v18
	v_add_u32_e32 v12, 0x600, v18
	s_mul_i32 s18, s15, 0x5c00
	s_mul_hi_u32 s19, s14, 0x5c00
	s_add_i32 s19, s19, s18
	s_mul_i32 s18, s14, 0x5c00
	s_add_u32 s18, s26, s18
	s_addc_u32 s19, s27, s19
	s_lshl_b32 s20, s17, 9
	s_add_u32 s20, s18, s20
	v_and_b32_e32 v87, 31, v18
	s_addc_u32 s21, s19, 0
	s_add_u32 s18, s20, 0x2280
	v_ashrrev_i32_e32 v86, 5, v18
	s_addc_u32 s19, s21, 0
	v_ashrrev_i32_e32 v88, 5, v10
	v_ashrrev_i32_e32 v90, 5, v11
	v_ashrrev_i32_e32 v92, 5, v12
	v_readfirstlane_b32 s17, v18
	s_ashr_i32 s17, s17, 6
	v_bfe_u32 v24, v18, 4, 2
	v_lshl_or_b32 v126, s17, 4, v19
	v_ashrrev_i32_e32 v127, 31, v126
	v_mov_b64_e32 v[22:23], s[18:19]
	v_lshlrev_b32_e32 v20, 4, v24
	v_mov_b32_e32 v21, v1
	v_bfe_u32 v146, v18, 2, 2
	v_lshlrev_b32_e32 v144, 2, v24
	v_or_b32_e32 v91, v144, v146
	s_cmp_lt_i32 s17, 0
	v_ashrrev_i32_e32 v8, 4, v10
	v_ashrrev_i32_e32 v9, 31, v8
	v_lshlrev_b64 v[2:3], 10, v[8:9]
	v_lshl_add_u64 v[2:3], v[6:7], 0, v[2:3]
	global_load_dwordx4 v[30:33], v[2:3], off
	v_mad_u32_u24 v75, v8, s77, v0
	v_ashrrev_i32_e32 v8, 4, v11
	v_ashrrev_i32_e32 v9, 31, v8
	v_lshlrev_b64 v[2:3], 10, v[8:9]
	v_lshl_add_u64 v[2:3], v[6:7], 0, v[2:3]
	global_load_dwordx4 v[34:37], v[2:3], off
	v_mad_u32_u24 v76, v8, s77, v0
	v_ashrrev_i32_e32 v8, 4, v12
	v_ashrrev_i32_e32 v9, 31, v8
	v_lshlrev_b64 v[2:3], 10, v[8:9]
	v_lshl_add_u64 v[2:3], v[6:7], 0, v[2:3]
	global_load_dwordx4 v[38:41], v[2:3], off
	v_mad_u32_u24 v77, v8, s77, v0
	v_lshlrev_b32_e32 v0, 4, v87
	v_mul_lo_u32 v8, v86, s97
	v_lshl_add_u64 v[2:3], s[20:21], 0, v[0:1]
	v_lshl_add_u64 v[6:7], v[2:3], 0, s[66:67]
	v_mad_i64_i32 v[2:3], s[20:21], v86, s71, v[6:7]
	global_load_dwordx4 v[42:45], v[2:3], off
	v_add_u32_e32 v0, 0, v0
	v_add_u32_e32 v137, v0, v8
	v_mul_lo_u32 v8, v88, s97
	v_add_u32_e32 v138, v0, v8
	v_mul_lo_u32 v8, v90, s97
	v_add_u32_e32 v139, v0, v8
	v_mul_lo_u32 v8, v92, s97
	v_add_u32_e32 v140, v0, v8
	v_mad_i64_i32 v[2:3], s[20:21], v88, s71, v[6:7]
	global_load_dwordx4 v[46:49], v[2:3], off
	v_mad_i64_i32 v[2:3], s[20:21], v90, s71, v[6:7]
	global_load_dwordx4 v[50:53], v[2:3], off
	v_mad_i64_i32 v[2:3], s[20:21], v92, s71, v[6:7]
	global_load_dwordx4 v[54:57], v[2:3], off
	v_add_u32_e32 v2, 0x800, v18
	v_ashrrev_i32_e32 v94, 5, v2
	v_mad_i64_i32 v[2:3], s[20:21], v94, s71, v[6:7]
	global_load_dwordx4 v[58:61], v[2:3], off
	v_mul_lo_u32 v8, v94, s97
	v_add_u32_e32 v141, v0, v8
	v_add_u32_e32 v2, 0xa00, v18
	v_ashrrev_i32_e32 v130, 5, v2
	v_mad_i64_i32 v[2:3], s[20:21], v130, s71, v[6:7]
	global_load_dwordx4 v[62:65], v[2:3], off
	v_mul_lo_u32 v8, v130, s97
	v_add_u32_e32 v142, v0, v8
	v_add_u32_e32 v2, 0xc00, v18
	v_ashrrev_i32_e32 v132, 5, v2
	v_mad_i64_i32 v[2:3], s[20:21], v132, s71, v[6:7]
	global_load_dwordx4 v[66:69], v[2:3], off
	v_mul_lo_u32 v8, v132, s97
	v_add_u32_e32 v143, v0, v8
	v_add_u32_e32 v2, 0xe00, v18
	v_ashrrev_i32_e32 v134, 5, v2
	v_mad_i64_i32 v[2:3], s[20:21], v134, s71, v[6:7]
	global_load_dwordx4 v[70:73], v[2:3], off
	v_mul_lo_u32 v6, v134, s97
	v_add_u32_e32 v145, v0, v6
	v_lshlrev_b32_e32 v0, 3, v24
	v_lshlrev_b32_e32 v18, 3, v18
	v_and_b32_e32 v18, 24, v18
	v_add_u32_e32 v147, 0, v18
	v_mad_u32_u24 v93, v91, s97, v147
	v_lshlrev_b64 v[2:3], 10, v[126:127]
	v_lshl_add_u64 v[2:3], s[8:9], 0, v[2:3]
	v_mad_i64_i32 v[22:23], s[8:9], v126, s71, v[22:23]
	v_lshl_add_u64 v[2:3], v[2:3], 0, v[20:21]
	v_lshl_add_u64 v[22:23], v[22:23], 0, v[0:1]
	global_load_dwordx4 v[14:17], v[2:3], off
	global_load_dwordx4 v[10:13], v[2:3], off offset:64
	global_load_dwordx4 v[6:9], v[2:3], off offset:128
	s_nop 0
	global_load_dwordx4 v[2:5], v[2:3], off offset:192
	s_nop 0
	global_load_dwordx2 v[128:129], v[22:23], off
	global_load_dwordx2 v[124:125], v[22:23], off offset:32
	global_load_dwordx2 v[122:123], v[22:23], off offset:64
	global_load_dwordx2 v[120:121], v[22:23], off offset:96
	global_load_dwordx2 v[118:119], v[22:23], off offset:128
	global_load_dwordx2 v[116:117], v[22:23], off offset:160
	global_load_dwordx2 v[114:115], v[22:23], off offset:192
	global_load_dwordx2 v[112:113], v[22:23], off offset:224
	global_load_dwordx2 v[110:111], v[22:23], off offset:256
	global_load_dwordx2 v[108:109], v[22:23], off offset:288
	global_load_dwordx2 v[106:107], v[22:23], off offset:320
	global_load_dwordx2 v[104:105], v[22:23], off offset:352
	global_load_dwordx2 v[102:103], v[22:23], off offset:384
	global_load_dwordx2 v[100:101], v[22:23], off offset:416
	global_load_dwordx2 v[98:99], v[22:23], off offset:448
	global_load_dwordx2 v[96:97], v[22:23], off offset:480
	v_add_u32_e32 v20, 0, v20
	v_mad_u32_u24 v89, v19, s77, v20
	s_waitcnt vmcnt(31)
	ds_write_b128 v74, v[26:29]
	s_waitcnt vmcnt(30)
	ds_write_b128 v75, v[30:33]
	s_waitcnt vmcnt(29)
	ds_write_b128 v76, v[34:37]
	s_waitcnt vmcnt(28)
	ds_write_b128 v77, v[38:41]
	s_waitcnt vmcnt(27)
	ds_write_b128 v137, v[42:45] offset:34816
	s_waitcnt vmcnt(26)
	ds_write_b128 v138, v[46:49] offset:34816
	s_waitcnt vmcnt(25)
	ds_write_b128 v139, v[50:53] offset:34816
	s_waitcnt vmcnt(24)
	ds_write_b128 v140, v[54:57] offset:34816
	s_waitcnt vmcnt(23)
	ds_write_b128 v141, v[58:61] offset:34816
	s_waitcnt vmcnt(22)
	ds_write_b128 v142, v[62:65] offset:34816
	s_waitcnt vmcnt(21)
	ds_write_b128 v143, v[66:69] offset:34816
	s_waitcnt vmcnt(20)
	ds_write_b128 v145, v[70:73] offset:34816
	s_waitcnt lgkmcnt(0)
	s_barrier
; #define LAS __attribute__((address_space(3)))
; __device__ __forceinline__ float ex2(float x) { return __builtin_amdgcn_exp2f(x); }
; __device__ __forceinline__ s16x4 tr_read(LAS const unsigned char* p) { return __builtin_bit_cast(s16x4, __builtin_amdgcn_ds_read_tr16_b64_v4i16((LAS v4i16_t*)p)); }
; __device__ __forceinline__ bf16x8 pack_p(const f32x4 a, const f32x4 b) { v4u w; w.x = pk2(a[0], a[1]); w.y = pk2(a[2], a[3]); w.z = pk2(b[0], b[1]); w.w = pk2(b[2], b[3]); return __builtin_bit_cast(bf16x8, w); }
; #define MFMA16(a, b, c) __builtin_amdgcn_mfma_f32_16x16x32_bf16((a), (b), (c), 0, 0, 0)
; __device__ __forceinline__ void ret_out_unit(LAS unsigned char* lds, const bf16* Qp, const bf16* Kp, const bf16* Vp, const bf16* Sp  , const bf16* Gp  ,
;                                              gfp gn  , bf16* Op, float lg2, int tid) {
;     ...
;     for (int tp = 0; tp < 4; ++tp) {
;         if (2 * tp <= w) {
;             f32x4 s[2];
; #pragma unroll
;             for (int u = 0; u < 2; ++u) { const int t = 2 * tp + u; s[u] = (f32x4){0.f, 0.f, 0.f, 0.f};
; #pragma unroll
;                 for (int ks = 0; ks < 4; ++ks) { const bf16x8 kf = *(const LAS bf16x8*)(lds + KOFF + (16 * t + c16) * SKk + (32 * ks + 8 * g) * 2); s[u] = MFMA16(kf, qf[ks], s[u]); }
; #pragma unroll
;                 for (int r = 0; r < 4; ++r) { const int d = ql - (16 * t + 4 * g + r); s[u][r] = d >= 0 ? s[u][r] * ex2((float)d * lg2) : 0.f; } }
;             const bf16x8 pf = pack_p(s[0], s[1]);
;             const LAS unsigned char* v0 = lds + VOFF + (32 * tp + 4 * g + (c16 >> 2)) * SVv + (4 * (c16 & 3)) * 2;
; #pragma unroll
;             for (int n = 0; n < 16; ++n) { const bf16x8 vf = cat4(tr_read(v0 + n * 32), tr_read(v0 + 16 * SVv + n * 32)); acc_o[n] = MFMA16(vf, pf, acc_o[n]); }
	s_cbranch_scc1 .LBB0_764
	ds_read_b128 v[18:21], v89
	ds_read_b128 v[22:25], v89 offset:64
	ds_read_b128 v[26:29], v89 offset:128
	ds_read_b128 v[30:33], v89 offset:192
	v_sub_u32_e32 v34, v126, v144
	s_waitcnt vmcnt(19) lgkmcnt(3)
	v_mfma_f32_16x16x32_bf16 v[18:21], v[18:21], v[14:17], 0
	v_xad_u32 v35, v144, -1, v126
	v_or_b32_e32 v36, 2, v144
	v_cvt_f32_u32_e32 v37, v34
	s_waitcnt vmcnt(18) lgkmcnt(2)
	v_mfma_f32_16x16x32_bf16 v[18:21], v[22:25], v[10:13], v[18:21]
	v_cvt_f32_u32_e32 v38, v35
	v_sub_u32_e32 v36, v126, v36
	v_cvt_f32_u32_e32 v39, v36
	s_waitcnt vmcnt(17) lgkmcnt(1)
	v_mfma_f32_16x16x32_bf16 v[18:21], v[26:29], v[6:9], v[18:21]
	v_mul_f32_e32 v37, v136, v37
	v_mul_f32_e32 v22, v136, v38
	v_exp_f32_e32 v37, v37
	v_exp_f32_e32 v38, v22
	v_mul_f32_e32 v22, v136, v39
	s_waitcnt vmcnt(16) lgkmcnt(0)
	v_mfma_f32_16x16x32_bf16 v[18:21], v[30:33], v[2:5], v[18:21]
	v_exp_f32_e32 v39, v22
	ds_read_b128 v[22:25], v89 offset:4352
	v_or_b32_e32 v26, 3, v144
	v_cmp_lt_i32_e32 vcc, -1, v34
	ds_read_b128 v[30:33], v89 offset:4480
	s_nop 2
	v_mul_f32_e32 v18, v37, v18
	v_sub_u32_e32 v37, v126, v26
	v_cndmask_b32_e32 v34, 0, v18, vcc
	v_cvt_f32_u32_e32 v18, v37
	ds_read_b128 v[26:29], v89 offset:4416
	s_waitcnt lgkmcnt(2)
	v_mfma_f32_16x16x32_bf16 v[22:25], v[22:25], v[14:17], 0
	v_mul_f32_e32 v19, v38, v19
	v_mul_f32_e32 v18, v136, v18
	v_exp_f32_e32 v18, v18
	v_cmp_lt_i32_e32 vcc, -1, v35
	v_mul_f32_e32 v38, v18, v21
	s_nop 0
	v_cndmask_b32_e32 v35, 0, v19, vcc
	v_mul_f32_e32 v19, v39, v20
	v_cmp_lt_i32_e32 vcc, -1, v36
	v_cvt_pk_bf16_f32 v66, v34, v35
	s_nop 1
	v_cndmask_b32_e32 v36, 0, v19, vcc
	s_waitcnt lgkmcnt(0)
	v_mfma_f32_16x16x32_bf16 v[18:21], v[26:29], v[10:13], v[22:25]
	v_or_b32_e32 v26, 16, v144
	v_sub_u32_e32 v26, v126, v26
	v_or_b32_e32 v29, 17, v144
	ds_read_b128 v[22:25], v89 offset:4544
	v_cvt_f32_u32_e32 v27, v26
	v_sub_u32_e32 v29, v126, v29
	v_mfma_f32_16x16x32_bf16 v[18:21], v[30:33], v[6:9], v[18:21]
	v_cvt_f32_u32_e32 v30, v29
	v_mul_f32_e32 v27, v136, v27
	v_exp_f32_e32 v27, v27
	s_waitcnt lgkmcnt(0)
	v_mfma_f32_16x16x32_bf16 v[18:21], v[22:25], v[2:5], v[18:21]
	v_mul_f32_e32 v22, v136, v30
	v_exp_f32_e32 v22, v22
	v_or_b32_e32 v23, 18, v144
	v_sub_u32_e32 v23, v126, v23
	v_cmp_lt_i32_e32 vcc, -1, v37
	v_cvt_f32_u32_e32 v24, v23
	s_nop 1
	v_mul_f32_e32 v18, v27, v18
	v_cndmask_b32_e32 v28, 0, v38, vcc
	v_cmp_lt_i32_e32 vcc, -1, v26
	v_cvt_pk_bf16_f32 v67, v36, v28
	s_nop 1
	v_cndmask_b32_e32 v25, 0, v18, vcc
	v_mul_f32_e32 v18, v22, v19
	v_or_b32_e32 v22, 19, v144
	v_sub_u32_e32 v22, v126, v22
	v_mul_f32_e32 v19, v136, v24
	v_cvt_f32_u32_e32 v24, v22
	v_cmp_lt_i32_e32 vcc, -1, v29
	v_exp_f32_e32 v19, v19
	s_nop 0
	v_cndmask_b32_e32 v26, 0, v18, vcc
	v_mul_f32_e32 v18, v136, v24
	v_exp_f32_e32 v18, v18
	v_mul_f32_e32 v19, v19, v20
	v_cmp_lt_i32_e32 vcc, -1, v23
	v_cvt_pk_bf16_f32 v68, v25, v26
	v_mul_f32_e32 v18, v18, v21
	s_nop 0
	v_cndmask_b32_e32 v23, 0, v19, vcc
	v_cmp_lt_i32_e32 vcc, -1, v22
	s_nop 1
	v_cndmask_b32_e32 v22, 0, v18, vcc
	ds_read_b64_tr_b16 v[20:21], v93 offset:43520
	ds_read_b64_tr_b16 v[18:19], v93 offset:34816
	v_cvt_pk_bf16_f32 v69, v23, v22
	ds_read_b64_tr_b16 v[24:25], v93 offset:43552
	ds_read_b64_tr_b16 v[22:23], v93 offset:34848
	ds_read_b64_tr_b16 v[34:35], v93 offset:34880
	ds_read_b64_tr_b16 v[38:39], v93 offset:34912
	ds_read_b64_tr_b16 v[36:37], v93 offset:43584
	ds_read_b64_tr_b16 v[40:41], v93 offset:43616
	s_waitcnt lgkmcnt(6)
	v_mfma_f32_16x16x32_bf16 v[30:33], v[18:21], v[66:69], 0
	s_waitcnt lgkmcnt(4)
	v_mfma_f32_16x16x32_bf16 v[26:29], v[22:25], v[66:69], 0
	s_waitcnt lgkmcnt(1)
	v_mfma_f32_16x16x32_bf16 v[22:25], v[34:37], v[66:69], 0
	ds_read_b64_tr_b16 v[34:35], v93 offset:34944
	ds_read_b64_tr_b16 v[36:37], v93 offset:43648
	s_waitcnt lgkmcnt(2)
	v_mfma_f32_16x16x32_bf16 v[18:21], v[38:41], v[66:69], 0
	ds_read_b64_tr_b16 v[40:41], v93 offset:43680
	ds_read_b64_tr_b16 v[38:39], v93 offset:34976
	ds_read_b64_tr_b16 v[42:43], v93 offset:35008
	ds_read_b64_tr_b16 v[46:47], v93 offset:35040
	ds_read_b64_tr_b16 v[44:45], v93 offset:43712
	ds_read_b64_tr_b16 v[48:49], v93 offset:43744
	ds_read_b64_tr_b16 v[50:51], v93 offset:35072
	ds_read_b64_tr_b16 v[52:53], v93 offset:43776
	ds_read_b64_tr_b16 v[56:57], v93 offset:43808
	ds_read_b64_tr_b16 v[54:55], v93 offset:35104
	ds_read_b64_tr_b16 v[58:59], v93 offset:35136
	ds_read_b64_tr_b16 v[62:63], v93 offset:35168
	ds_read_b64_tr_b16 v[60:61], v93 offset:43840
	ds_read_b64_tr_b16 v[64:65], v93 offset:43872
	ds_read_b64_tr_b16 v[70:71], v93 offset:35200
	ds_read_b64_tr_b16 v[72:73], v93 offset:43904
	ds_read_b64_tr_b16 v[76:77], v93 offset:43936
	ds_read_b64_tr_b16 v[74:75], v93 offset:35232
	ds_read_b64_tr_b16 v[78:79], v93 offset:35264
	ds_read_b64_tr_b16 v[82:83], v93 offset:35296
	ds_read_b64_tr_b16 v[80:81], v93 offset:43968
	ds_read_b64_tr_b16 v[84:85], v93 offset:44000
	s_waitcnt lgkmcnt(14)
	v_mfma_f32_16x16x32_bf16 v[34:37], v[34:37], v[66:69], 0
	v_mfma_f32_16x16x32_bf16 v[38:41], v[38:41], v[66:69], 0
	v_mfma_f32_16x16x32_bf16 v[42:45], v[42:45], v[66:69], 0
	v_mfma_f32_16x16x32_bf16 v[46:49], v[46:49], v[66:69], 0
	v_mfma_f32_16x16x32_bf16 v[50:53], v[50:53], v[66:69], 0
	s_waitcnt lgkmcnt(12)
	v_mfma_f32_16x16x32_bf16 v[54:57], v[54:57], v[66:69], 0
	s_waitcnt lgkmcnt(9)
	v_mfma_f32_16x16x32_bf16 v[58:61], v[58:61], v[66:69], 0
	s_waitcnt lgkmcnt(8)
	v_mfma_f32_16x16x32_bf16 v[62:65], v[62:65], v[66:69], 0
	s_waitcnt lgkmcnt(6)
	v_mfma_f32_16x16x32_bf16 v[70:73], v[70:73], v[66:69], 0
	s_waitcnt lgkmcnt(4)
	v_mfma_f32_16x16x32_bf16 v[74:77], v[74:77], v[66:69], 0
	s_waitcnt lgkmcnt(1)
	v_mfma_f32_16x16x32_bf16 v[78:81], v[78:81], v[66:69], 0
	s_waitcnt lgkmcnt(0)
	v_mfma_f32_16x16x32_bf16 v[66:69], v[82:85], v[66:69], 0
	s_cmp_lt_i32 s17, 2
	s_cbranch_scc0 .LBB0_765
	s_branch .LBB0_766
